# LDS-DMA K-loops (2 swizzled 32KiB stages, 1 barrier/step) for ffn-down and out-proj residual GEMMs, on top of DMA gate/up + in-proj and XCD remap
# speedup vs baseline: 1.0419x; 1.0259x over previous
; DI int tid_l() { int t = threadIdx.x; asm volatile("" : "+v"(t)); return t; }
; DI int bid_l() { int t = blockIdx.x; asm volatile("" : "+s"(t)); return t; }
; template <int MF, int BK, class Epi>
; DI void gemm_phase_t(char* lds, const GemmDesc g, const Epi epi) {
;   constexpr int BM = MF * 64, LS = BK + 8, CPR = BK / 8, RSTEP = 256 / CPR;
;   constexpr int APT = BM * CPR / 256, BPT = 128 * CPR / 256, STG = (BM + 128) * LS, NKK = BK / 16;
;   u16* sbase = (u16*)lds;
;   const int tid = tid_l(), lane = tid & 63, w = tid >> 6, wm = w >> 1, wn = w & 1, l31 = lane & 31, h = lane >> 5;
;   const int ntn = g.Npad / 128, ntm = g.M / BM, ntiles = ntm * ntn, nk = g.K / BK;
;   const int lr = tid / CPR, lc = tid % CPR;
;   for (int t = bid_l(); t < ntiles; t += gridDim.x) {
;     const int tn = t % ntn, tm = t / ntn;
;     const int m0 = tm * BM, n0 = tn * 128;
;     const u16* Ap = g.A + (size_t)(m0 + lr) * g.lda + lc * 8;
;     const u16* Bp = g.Bt + (size_t)(n0 + lr) * g.ldb + lc * 8;
; DI void run_phase(const Params& p, char* lds, int ph) {
;     ...
;   int layer, sub;
;   { const int q = ph - 1;
;     if (q < 11) { layer = 0; sub = q; } else if (q < 21) { layer = 1; sub = q - 11; } else if (q < 32) { layer = 2; sub = q - 21; } else { layer = 3; sub = q - 32; }
;     if ((layer & 1) && sub >= 6) sub += 1; }
;   const bool even = (layer & 1) == 0;
;   const int e = layer >> 1;
;   const bool need_ctx = layer < 3;
;   const int rows = need_ctx ? TA : TL;
;   const float* modl = (const float*)(ws + OFF_MOD) + (size_t)layer * 9 * 6144;
;   const float* res_lat = layer == 0 ? p.in[0] : p.out;
;   const float* res_ctx = layer == 0 ? p.in[2] : (const float*)(ws + OFF_HCTX);
;   switch (sub) {
.LBB0_27:
	v_readlane_b32 s8, v251, 7
	v_readlane_b32 s10, v251, 9
	v_readlane_b32 s6, v253, 30
	s_xor_b64 s[38:39], s[2:3], -1
	s_add_i32 s4, s4, s10
	s_and_b32 s5, s6, 1
	v_readlane_b32 s9, v251, 8
	s_bitcmp1_b32 s6, 0
	s_cselect_b64 s[8:9], -1, 0
	s_cmp_gt_i32 s4, 5
	s_cselect_b64 s[2:3], -1, 0
	v_writelane_b32 v253, s8, 33
	s_and_b64 s[2:3], s[2:3], s[8:9]
	v_cndmask_b32_e64 v2, 0, 1, s[2:3]
	v_writelane_b32 v253, s9, 34
	v_readfirstlane_b32 s2, v2
	s_add_i32 s4, s4, s2
	s_cmp_eq_u32 s5, 0
	s_cselect_b64 s[20:21], -1, 0
	s_lshr_b32 s2, s6, 1
	v_writelane_b32 v253, s2, 35
	s_mul_i32 s2, s6, 0x36000
	s_add_u32 s2, s30, s2
	s_addc_u32 s3, s31, 0
	s_add_u32 s2, s2, 0x800000
	s_addc_u32 s3, s3, 0
	v_writelane_b32 v253, s2, 36
	s_cmp_lt_i32 s4, 5
	v_readlane_b32 s11, v251, 10
	v_writelane_b32 v253, s3, 37
	v_writelane_b32 v253, s4, 38
	s_mov_b64 s[4:5], 0
	v_writelane_b32 v253, s4, 39
	s_mov_b64 s[2:3], -1
	s_nop 0
	v_writelane_b32 v253, s5, 40
	s_cbranch_scc1 .LBB0_359
	v_readlane_b32 s2, v253, 31
	v_readlane_b32 s3, v253, 32
	s_and_b64 s[2:3], s[2:3], exec
	s_mov_b32 s2, 0x8800
	s_cselect_b32 s2, s2, 0x8000
	v_writelane_b32 v253, s2, 41
	s_nop 0
	v_readlane_b32 s2, v253, 38
	s_cmp_gt_i32 s2, 7
	s_cbranch_scc0 .LBB0_47
	s_cmp_gt_i32 s2, 8
	s_cbranch_scc0 .LBB0_48
	s_cmp_gt_i32 s2, 9
	s_mov_b64 s[2:3], -1
	s_cbranch_scc0 .LBB0_284
	v_writelane_b32 v253, s28, 42
	s_nop 1
	v_writelane_b32 v253, s29, 43
	v_writelane_b32 v253, s30, 44
	v_writelane_b32 v253, s31, 45
	v_writelane_b32 v253, s20, 16
	s_nop 1
	v_writelane_b32 v253, s21, 17
	v_writelane_b32 v253, s38, 46
	s_nop 1
	v_writelane_b32 v253, s39, 47
	s_nop 0
	v_readlane_b32 s2, v253, 38
	s_cmp_eq_u32 s2, 10
	s_cbranch_scc0 .LBB0_283
	v_readlane_b32 s2, v253, 36
	s_load_dwordx4 s[20:23], s[50:51], 0x108
	v_readlane_b32 s3, v253, 37
	s_add_u32 s2, s2, 0x5000
	v_readlane_b32 s4, v253, 16
	s_addc_u32 s3, s3, 0
	v_readlane_b32 s5, v253, 17
	s_and_b64 s[4:5], s[4:5], exec
	s_cselect_b32 s48, 0, 0x1c364000
	s_waitcnt lgkmcnt(0)
	s_add_u32 s4, s22, s48
	s_addc_u32 s5, s23, 0
	s_add_u32 s4, s4, 0x214c000
	s_addc_u32 s5, s5, 0
	v_mov_b32_e32 v4, v0
	v_readlane_b32 s6, v251, 0
	s_cmpk_gt_i32 s6, 0x7ff
	s_cbranch_scc1 .LBB0_37
	v_ashrrev_i32_e32 v2, 31, v4
	v_lshrrev_b32_e32 v2, 29, v2
	v_add_u32_e32 v5, v4, v2
	v_ashrrev_i32_e32 v2, 3, v5
	v_and_b32_e32 v5, -8, v5
	v_sub_u32_e32 v5, v4, v5
	v_lshlrev_b32_e32 v6, 3, v5
	v_ashrrev_i32_e32 v7, 31, v6
	v_lshlrev_b64 v[100:101], 1, v[6:7]
	v_lshl_add_u64 v[6:7], s[22:23], 0, v[100:101]
	s_mov_b64 s[8:9], 0x37ac000
	v_bfe_u32 v8, v4, 5, 1
	v_and_b32_e32 v9, 31, v4
	v_and_b32_e32 v10, 64, v4
	v_lshl_add_u64 v[102:103], v[6:7], 0, s[8:9]
	v_and_b32_e32 v6, 0x5f, v4
	v_ashrrev_i32_e32 v4, 1, v4
	s_movk_i32 s7, 0xffc0
	v_and_or_b32 v112, v4, s7, v9
	s_movk_i32 s7, 0x90
	v_mul_lo_u32 v4, v2, s7
	v_lshlrev_b32_e32 v5, 4, v5
	v_lshlrev_b32_e32 v7, 4, v8
	v_lshl_or_b32 v113, v8, 3, v10
	v_add_u32_e32 v8, 0x3600, v4
	v_mul_lo_u32 v9, v112, s7
	v_mul_u32_u24_e32 v6, 0x90, v6
	v_lshl_add_u64 v[104:105], s[4:5], 0, v[100:101]
	v_lshl_add_u64 v[106:107], s[48:49], 0, v[100:101]
	v_add_u32_e32 v114, v5, v4
	v_add_u32_e32 v115, v5, v8
	v_add_u32_e32 v116, v7, v6
	v_add_u32_e32 v117, v7, v9
	v_bfe_u32 v4, v0, 1, 3
	v_bfe_u32 v5, v0, 5, 1
	v_xor_b32_e32 v4, v4, v5
	v_lshlrev_b32_e32 v4, 4, v4
	v_add_u32_e32 v4, 0x100, v4
	v_and_b32_e32 v5, 31, v0
	v_bfe_u32 v6, v0, 7, 1
	v_lshl_or_b32 v6, v6, 6, v5
	v_lshl_add_u32 v114, v6, 7, v4
	v_bfe_u32 v6, v0, 6, 1
	v_lshl_or_b32 v6, v6, 6, v5
	v_lshl_add_u32 v234, v6, 7, v4
	v_add_u32_e32 v234, 0x4000, v234
	v_xor_b32_e32 v115, 0x20, v114
	v_xor_b32_e32 v235, 0x20, v234
	v_xor_b32_e32 v116, 0x40, v114
	v_xor_b32_e32 v236, 0x40, v234
	v_xor_b32_e32 v117, 0x60, v114
	v_xor_b32_e32 v237, 0x60, v234
	v_bfe_u32 v4, v0, 4, 3
	v_and_b32_e32 v5, 7, v0
	v_xor_b32_e32 v4, v4, v5
	v_lshlrev_b32_e32 v4, 4, v4
	v_bfe_u32 v5, v0, 3, 3
	s_movk_i32 s9, 0x1600
	v_mad_u32_u24 v108, v5, s9, v4
	v_add_u32_e32 v109, 0x2c000, v108
	v_add_u32_e32 v110, 0x58000, v108
	v_add_u32_e32 v111, 0x84000, v108
	v_lshrrev_b32_e32 v5, 6, v0
	v_lshlrev_b32_e32 v5, 10, v5
	v_add_u32_e32 v5, 0x100, v5
	s_nop 0
	v_readfirstlane_b32 s100, v5

; template <int MF, int BK, class Epi>
; DI void gemm_phase_t(char* lds, const GemmDesc g, const Epi epi) {
;     ...
;   for (int t = bid_l(); t < ntiles; t += gridDim.x) {
;     const int tn = t % ntn, tm = t / ntn;
;     const int m0 = tm * BM, n0 = tn * 128;
;     const u16* Ap = g.A + (size_t)(m0 + lr) * g.lda + lc * 8;
;     const u16* Bp = g.Bt + (size_t)(n0 + lr) * g.ldb + lc * 8;
;     u32x4 ra[APT], rb[BPT];
; #pragma unroll
;     for (int j = 0; j < APT; ++j) ra[j] = *(const u32x4*)(Ap + (size_t)j * RSTEP * g.lda);
; #pragma unroll
;     for (int j = 0; j < BPT; ++j) rb[j] = *(const u32x4*)(Bp + (size_t)j * RSTEP * g.ldb);
; #pragma unroll
;     for (int j = 0; j < APT; ++j) *(u32x4*)(sbase + (lr + RSTEP * j) * LS + lc * 8) = ra[j];
; #pragma unroll
;     for (int j = 0; j < BPT; ++j) *(u32x4*)(sbase + BM * LS + (lr + RSTEP * j) * LS + lc * 8) = rb[j];
;     if (nk > 1) {
; #pragma unroll
;       for (int j = 0; j < APT; ++j) ra[j] = *(const u32x4*)(Ap + (size_t)j * RSTEP * g.lda + BK);
; #pragma unroll
;       for (int j = 0; j < BPT; ++j) rb[j] = *(const u32x4*)(Bp + (size_t)j * RSTEP * g.ldb + BK);
;     }
;     f32x16 acc[MF][2];
; #pragma unroll
;     for (int i = 0; i < MF; ++i)
; #pragma unroll
;       for (int j = 0; j < 2; ++j) acc[i][j] = zero16();
;     for (int kt = 0; kt < nk; ++kt) {
;       __syncthreads();
;       const u16* sA = sbase + (kt & 1) * STG;
;       const u16* sB = sA + BM * LS;
;       if (kt + 1 < nk) {
;         u16* nA = sbase + ((kt + 1) & 1) * STG;
; #pragma unroll
;         for (int j = 0; j < APT; ++j) *(u32x4*)(nA + (lr + RSTEP * j) * LS + lc * 8) = ra[j];
; #pragma unroll
;         for (int j = 0; j < BPT; ++j) *(u32x4*)(nA + BM * LS + (lr + RSTEP * j) * LS + lc * 8) = rb[j];
;         if (kt + 2 < nk) {
; #pragma unroll
;           for (int j = 0; j < APT; ++j) ra[j] = *(const u32x4*)(Ap + (size_t)j * RSTEP * g.lda + (kt + 2) * BK);
; #pragma unroll
;           for (int j = 0; j < BPT; ++j) rb[j] = *(const u32x4*)(Bp + (size_t)j * RSTEP * g.ldb + (kt + 2) * BK);
;         }
;       }
;       bf16x8 af[NKK][MF], bfr[NKK][2];
; #pragma unroll
;       for (int kk = 0; kk < NKK; ++kk) {
; #pragma unroll
;         for (int ni = 0; ni < 2; ++ni) bfr[kk][ni] = *(const bf16x8*)(sB + (wn * 64 + ni * 32 + l31) * LS + kk * 16 + h * 8);
; #pragma unroll
.Lnomap_tl1:
	s_ashr_i32 s7, s98, 31
	s_lshr_b32 s7, s7, 29
	s_add_i32 s7, s98, s7
	s_and_b32 s8, s7, 0x1fffff8
	s_lshl_b32 s7, s7, 4
	s_and_b32 s7, s7, 0xffffff80
	v_add_u32_e32 v58, s7, v2
	s_movk_i32 s12, 0x1600
	v_mad_i64_i32 v[4:5], s[10:11], v58, s12, v[102:103]
	s_sub_i32 s8, s98, s8
	s_lshl_b32 s8, s8, 7
	v_add_u32_e32 v59, s8, v2
	v_mad_i64_i32 v[12:13], s[10:11], v59, s12, v[104:105]
	v_mov_b32_e32 v60, 0
	v_readfirstlane_b32 s12, v4
	v_readfirstlane_b32 s13, v5
	v_readfirstlane_b32 s14, v12
	v_readfirstlane_b32 s15, v13
	v_mov_b32_e32 v4, 0
	v_mov_b32_e32 v5, 0
	v_mov_b32_e32 v6, 0
	v_mov_b32_e32 v7, 0
	v_mov_b32_e32 v8, 0
	v_mov_b32_e32 v9, 0
	v_mov_b32_e32 v10, 0
	v_mov_b32_e32 v11, 0
	v_mov_b32_e32 v12, 0
	v_mov_b32_e32 v13, 0
	v_mov_b32_e32 v14, 0
	v_mov_b32_e32 v15, 0
	v_mov_b32_e32 v16, 0
	v_mov_b32_e32 v17, 0
	v_mov_b32_e32 v18, 0
	v_mov_b32_e32 v19, 0
	v_mov_b32_e32 v20, 0
	v_mov_b32_e32 v21, 0
	v_mov_b32_e32 v22, 0
	v_mov_b32_e32 v23, 0
	v_mov_b32_e32 v24, 0
	v_mov_b32_e32 v25, 0
	v_mov_b32_e32 v26, 0
	v_mov_b32_e32 v27, 0
	v_mov_b32_e32 v28, 0
	v_mov_b32_e32 v29, 0
	v_mov_b32_e32 v30, 0
	v_mov_b32_e32 v31, 0
	v_mov_b32_e32 v32, 0
	v_mov_b32_e32 v33, 0
	v_mov_b32_e32 v34, 0
	v_mov_b32_e32 v35, 0
	v_mov_b32_e32 v36, 0
	v_mov_b32_e32 v37, 0
	v_mov_b32_e32 v38, 0
	v_mov_b32_e32 v39, 0
	v_mov_b32_e32 v40, 0
	v_mov_b32_e32 v41, 0
	v_mov_b32_e32 v42, 0
	v_mov_b32_e32 v43, 0
	v_mov_b32_e32 v44, 0
	v_mov_b32_e32 v45, 0
	v_mov_b32_e32 v46, 0
	v_mov_b32_e32 v47, 0
	v_mov_b32_e32 v48, 0
	v_mov_b32_e32 v49, 0
	v_mov_b32_e32 v50, 0
	v_mov_b32_e32 v51, 0
	v_mov_b32_e32 v52, 0
	v_mov_b32_e32 v53, 0
	v_mov_b32_e32 v54, 0
	v_mov_b32_e32 v55, 0
	v_mov_b32_e32 v56, 0
	v_mov_b32_e32 v57, 0
	v_mov_b32_e32 v58, 0
	v_mov_b32_e32 v59, 0
	v_mov_b32_e32 v60, 0
	v_mov_b32_e32 v61, 0
	v_mov_b32_e32 v62, 0
	v_mov_b32_e32 v63, 0
	v_mov_b32_e32 v64, 0
	v_mov_b32_e32 v65, 0
	v_mov_b32_e32 v66, 0
	v_mov_b32_e32 v67, 0
	s_add_i32 m0, s100, 0x0
	s_nop 0
	global_load_lds_dwordx4 v108, s[12:13]
	s_add_i32 m0, s100, 0x1000
	s_nop 0
	global_load_lds_dwordx4 v109, s[12:13]
	s_add_i32 m0, s100, 0x2000
	s_nop 0
	global_load_lds_dwordx4 v110, s[12:13]
	s_add_i32 m0, s100, 0x3000
	s_nop 0
	global_load_lds_dwordx4 v111, s[12:13]
	s_add_i32 m0, s100, 0x4000
	s_nop 0
	global_load_lds_dwordx4 v108, s[14:15]
	s_add_i32 m0, s100, 0x5000
	s_nop 0
	global_load_lds_dwordx4 v109, s[14:15]
	s_add_i32 m0, s100, 0x6000
	s_nop 0
	global_load_lds_dwordx4 v110, s[14:15]
	s_add_i32 m0, s100, 0x7000
	s_nop 0
	global_load_lds_dwordx4 v111, s[14:15]
	s_add_u32 s12, s12, 0x80
	s_addc_u32 s13, s13, 0
	s_add_u32 s14, s14, 0x80
	s_addc_u32 s15, s15, 0
	s_waitcnt vmcnt(0)
	s_waitcnt lgkmcnt(0)
	s_barrier
	s_add_i32 m0, s100, 0x8000
	s_nop 0
	global_load_lds_dwordx4 v108, s[12:13]
	s_add_i32 m0, s100, 0x9000
	s_nop 0
	global_load_lds_dwordx4 v109, s[12:13]
	s_add_i32 m0, s100, 0xa000
	s_nop 0
	global_load_lds_dwordx4 v110, s[12:13]
	s_add_i32 m0, s100, 0xb000
	s_nop 0
	global_load_lds_dwordx4 v111, s[12:13]
	s_add_i32 m0, s100, 0xc000
	s_nop 0
	global_load_lds_dwordx4 v108, s[14:15]
	s_add_i32 m0, s100, 0xd000
	s_nop 0
	global_load_lds_dwordx4 v109, s[14:15]
	s_add_i32 m0, s100, 0xe000
	s_nop 0
	global_load_lds_dwordx4 v110, s[14:15]
	s_add_i32 m0, s100, 0xf000
	s_nop 0
	global_load_lds_dwordx4 v111, s[14:15]
	s_add_u32 s12, s12, 0x80
	s_addc_u32 s13, s13, 0
	s_add_u32 s14, s14, 0x80
	s_addc_u32 s15, s15, 0
	ds_read_b128 v[68:71], v234
	ds_read_b128 v[72:75], v234 offset:4096
	ds_read_b128 v[76:79], v114
	ds_read_b128 v[80:83], v114 offset:4096
	ds_read_b128 v[84:87], v235
	ds_read_b128 v[88:91], v235 offset:4096
	ds_read_b128 v[92:95], v115
	ds_read_b128 v[96:99], v115 offset:4096
	ds_read_b128 v[118:121], v236
	ds_read_b128 v[122:125], v236 offset:4096
	ds_read_b128 v[126:129], v116
	ds_read_b128 v[130:133], v116 offset:4096
	ds_read_b128 v[134:137], v237
	ds_read_b128 v[138:141], v237 offset:4096
	ds_read_b128 v[142:145], v117
	ds_read_b128 v[146:149], v117 offset:4096
	s_movk_i32 s9, 21
.Ldma_dn_loop:
	s_waitcnt vmcnt(0)
	s_waitcnt lgkmcnt(0)
	s_barrier
	s_add_i32 m0, s100, 0x0
	s_nop 0
	global_load_lds_dwordx4 v108, s[12:13]
	s_add_i32 m0, s100, 0x1000
	s_nop 0
	global_load_lds_dwordx4 v109, s[12:13]
	s_add_i32 m0, s100, 0x2000
	s_nop 0
	global_load_lds_dwordx4 v110, s[12:13]
	s_add_i32 m0, s100, 0x3000
	s_nop 0
	global_load_lds_dwordx4 v111, s[12:13]
	s_add_i32 m0, s100, 0x4000
	s_nop 0
	global_load_lds_dwordx4 v108, s[14:15]
	s_add_i32 m0, s100, 0x5000
	s_nop 0
	global_load_lds_dwordx4 v109, s[14:15]
	s_add_i32 m0, s100, 0x6000
	s_nop 0
	global_load_lds_dwordx4 v110, s[14:15]
	s_add_i32 m0, s100, 0x7000
	s_nop 0
	global_load_lds_dwordx4 v111, s[14:15]
	s_add_u32 s12, s12, 0x80
	s_addc_u32 s13, s13, 0
	s_add_u32 s14, s14, 0x80
	s_addc_u32 s15, s15, 0
	ds_read_b128 v[150:153], v234 offset:32768
	ds_read_b128 v[154:157], v234 offset:36864
	ds_read_b128 v[158:161], v114 offset:32768
	ds_read_b128 v[162:165], v114 offset:36864
	ds_read_b128 v[168:171], v235 offset:32768
	ds_read_b128 v[172:175], v235 offset:36864
	ds_read_b128 v[176:179], v115 offset:32768
	ds_read_b128 v[180:183], v115 offset:36864
	ds_read_b128 v[184:187], v236 offset:32768
	ds_read_b128 v[188:191], v236 offset:36864
	ds_read_b128 v[192:195], v116 offset:32768
	ds_read_b128 v[198:201], v116 offset:36864
	ds_read_b128 v[218:221], v237 offset:32768
	ds_read_b128 v[222:225], v237 offset:36864
	ds_read_b128 v[226:229], v117 offset:32768
	ds_read_b128 v[230:233], v117 offset:36864
	v_mfma_f32_32x32x16_bf16 v[52:67], v[68:71], v[76:79], v[52:67]
	v_mfma_f32_32x32x16_bf16 v[36:51], v[72:75], v[76:79], v[36:51]
	v_mfma_f32_32x32x16_bf16 v[20:35], v[68:71], v[80:83], v[20:35]
	v_mfma_f32_32x32x16_bf16 v[4:19], v[72:75], v[80:83], v[4:19]
	v_mfma_f32_32x32x16_bf16 v[52:67], v[84:87], v[92:95], v[52:67]
	v_mfma_f32_32x32x16_bf16 v[36:51], v[88:91], v[92:95], v[36:51]
	v_mfma_f32_32x32x16_bf16 v[20:35], v[84:87], v[96:99], v[20:35]
	v_mfma_f32_32x32x16_bf16 v[4:19], v[88:91], v[96:99], v[4:19]
	v_mfma_f32_32x32x16_bf16 v[52:67], v[118:121], v[126:129], v[52:67]
	v_mfma_f32_32x32x16_bf16 v[36:51], v[122:125], v[126:129], v[36:51]
	v_mfma_f32_32x32x16_bf16 v[20:35], v[118:121], v[130:133], v[20:35]
	v_mfma_f32_32x32x16_bf16 v[4:19], v[122:125], v[130:133], v[4:19]
	v_mfma_f32_32x32x16_bf16 v[52:67], v[134:137], v[142:145], v[52:67]
	v_mfma_f32_32x32x16_bf16 v[36:51], v[138:141], v[142:145], v[36:51]
	v_mfma_f32_32x32x16_bf16 v[20:35], v[134:137], v[146:149], v[20:35]
	v_mfma_f32_32x32x16_bf16 v[4:19], v[138:141], v[146:149], v[4:19]
	s_waitcnt vmcnt(0)
	s_waitcnt lgkmcnt(0)
	s_barrier
; template <int MF, int BK, class Epi>
; DI void gemm_phase_t(char* lds, const GemmDesc g, const Epi epi) {
;     ...
;     for (int kt = 0; kt < nk; ++kt) {
;       __syncthreads();
;       const u16* sA = sbase + (kt & 1) * STG;
;       const u16* sB = sA + BM * LS;
;       if (kt + 1 < nk) {
;         u16* nA = sbase + ((kt + 1) & 1) * STG;
; #pragma unroll
;         for (int j = 0; j < APT; ++j) *(u32x4*)(nA + (lr + RSTEP * j) * LS + lc * 8) = ra[j];
; #pragma unroll
;         for (int j = 0; j < BPT; ++j) *(u32x4*)(nA + BM * LS + (lr + RSTEP * j) * LS + lc * 8) = rb[j];
;         if (kt + 2 < nk) {
; #pragma unroll
;           for (int j = 0; j < APT; ++j) ra[j] = *(const u32x4*)(Ap + (size_t)j * RSTEP * g.lda + (kt + 2) * BK);
; #pragma unroll
;           for (int j = 0; j < BPT; ++j) rb[j] = *(const u32x4*)(Bp + (size_t)j * RSTEP * g.ldb + (kt + 2) * BK);
;         }
;       }
;       bf16x8 af[NKK][MF], bfr[NKK][2];
; #pragma unroll
;       for (int kk = 0; kk < NKK; ++kk) {
; #pragma unroll
;         for (int ni = 0; ni < 2; ++ni) bfr[kk][ni] = *(const bf16x8*)(sB + (wn * 64 + ni * 32 + l31) * LS + kk * 16 + h * 8);
; #pragma unroll
;         for (int mi = 0; mi < MF; ++mi) af[kk][mi] = *(const bf16x8*)(sA + (wm * (MF * 32) + mi * 32 + l31) * LS + kk * 16 + h * 8);
;       }
;       __builtin_amdgcn_sched_barrier(0);
; #pragma unroll
;       for (int kk = 0; kk < NKK; ++kk)
; #pragma unroll
;         for (int mi = 0; mi < MF; ++mi)
; #pragma unroll
;           for (int ni = 0; ni < 2; ++ni) acc[mi][ni] = MFMA32(bfr[kk][ni], af[kk][mi], acc[mi][ni]);
;   template <int MF> DI void operator()(f32x16 (&acc)[MF][2], int mb, int nb, int l31, int h) const {
; #pragma unroll
;     for (int mi = 0; mi < MF; ++mi) {
;       const int row = mb + mi * 32 + l31;
;       const float* gr = gate + (size_t)modrow(row) * 6144;
;       const float* rp = row < TL ? res_lat + (size_t)row * D : res_ctx + (size_t)(row - TL) * D;
;       float* op = row < TL ? out_lat + (size_t)row * D : out_ctx + (size_t)(row - TL) * D;
; #pragma unroll
;       for (int g4 = 0; g4 < 4; ++g4)
; #pragma unroll
;         for (int ni = 0; ni < 2; ++ni) {
;           const int col0 = nb + 16 * g4 + 8 * h + 4 * ni;
;           const float4 gt = *(const float4*)(gr + col0);
;           const float4 rv = *(const float4*)(rp + col0);
	s_add_i32 m0, s100, 0x8000
	s_nop 0
	global_load_lds_dwordx4 v108, s[12:13]
	s_add_i32 m0, s100, 0x9000
	s_nop 0
	global_load_lds_dwordx4 v109, s[12:13]
	s_add_i32 m0, s100, 0xa000
	s_nop 0
	global_load_lds_dwordx4 v110, s[12:13]
	s_add_i32 m0, s100, 0xb000
	s_nop 0
	global_load_lds_dwordx4 v111, s[12:13]
	s_add_i32 m0, s100, 0xc000
	s_nop 0
	global_load_lds_dwordx4 v108, s[14:15]
	s_add_i32 m0, s100, 0xd000
	s_nop 0
	global_load_lds_dwordx4 v109, s[14:15]
	s_add_i32 m0, s100, 0xe000
	s_nop 0
	global_load_lds_dwordx4 v110, s[14:15]
	s_add_i32 m0, s100, 0xf000
	s_nop 0
	global_load_lds_dwordx4 v111, s[14:15]
	s_add_u32 s12, s12, 0x80
	s_addc_u32 s13, s13, 0
	s_add_u32 s14, s14, 0x80
	s_addc_u32 s15, s15, 0
	ds_read_b128 v[68:71], v234
	ds_read_b128 v[72:75], v234 offset:4096
	ds_read_b128 v[76:79], v114
	ds_read_b128 v[80:83], v114 offset:4096
	ds_read_b128 v[84:87], v235
	ds_read_b128 v[88:91], v235 offset:4096
	ds_read_b128 v[92:95], v115
	ds_read_b128 v[96:99], v115 offset:4096
	ds_read_b128 v[118:121], v236
	ds_read_b128 v[122:125], v236 offset:4096
	ds_read_b128 v[126:129], v116
	ds_read_b128 v[130:133], v116 offset:4096
	ds_read_b128 v[134:137], v237
	ds_read_b128 v[138:141], v237 offset:4096
	ds_read_b128 v[142:145], v117
	ds_read_b128 v[146:149], v117 offset:4096
	v_mfma_f32_32x32x16_bf16 v[52:67], v[150:153], v[158:161], v[52:67]
	v_mfma_f32_32x32x16_bf16 v[36:51], v[154:157], v[158:161], v[36:51]
	v_mfma_f32_32x32x16_bf16 v[20:35], v[150:153], v[162:165], v[20:35]
	v_mfma_f32_32x32x16_bf16 v[4:19], v[154:157], v[162:165], v[4:19]
	v_mfma_f32_32x32x16_bf16 v[52:67], v[168:171], v[176:179], v[52:67]
	v_mfma_f32_32x32x16_bf16 v[36:51], v[172:175], v[176:179], v[36:51]
	v_mfma_f32_32x32x16_bf16 v[20:35], v[168:171], v[180:183], v[20:35]
	v_mfma_f32_32x32x16_bf16 v[4:19], v[172:175], v[180:183], v[4:19]
	v_mfma_f32_32x32x16_bf16 v[52:67], v[184:187], v[192:195], v[52:67]
	v_mfma_f32_32x32x16_bf16 v[36:51], v[188:191], v[192:195], v[36:51]
	v_mfma_f32_32x32x16_bf16 v[20:35], v[184:187], v[198:201], v[20:35]
	v_mfma_f32_32x32x16_bf16 v[4:19], v[188:191], v[198:201], v[4:19]
	v_mfma_f32_32x32x16_bf16 v[52:67], v[218:221], v[226:229], v[52:67]
	v_mfma_f32_32x32x16_bf16 v[36:51], v[222:225], v[226:229], v[36:51]
	v_mfma_f32_32x32x16_bf16 v[20:35], v[218:221], v[230:233], v[20:35]
	v_mfma_f32_32x32x16_bf16 v[4:19], v[222:225], v[230:233], v[4:19]
	s_add_i32 s9, s9, -1
	s_cmp_lg_u32 s9, 0
	s_cbranch_scc1 .Ldma_dn_loop
	s_waitcnt vmcnt(0)
	s_waitcnt lgkmcnt(0)
	s_barrier
	ds_read_b128 v[150:153], v234 offset:32768
	ds_read_b128 v[154:157], v234 offset:36864
	ds_read_b128 v[158:161], v114 offset:32768
	ds_read_b128 v[162:165], v114 offset:36864
	ds_read_b128 v[168:171], v235 offset:32768
	ds_read_b128 v[172:175], v235 offset:36864
	ds_read_b128 v[176:179], v115 offset:32768
	ds_read_b128 v[180:183], v115 offset:36864
	ds_read_b128 v[184:187], v236 offset:32768
	ds_read_b128 v[188:191], v236 offset:36864
	ds_read_b128 v[192:195], v116 offset:32768
	ds_read_b128 v[198:201], v116 offset:36864
	ds_read_b128 v[218:221], v237 offset:32768
	ds_read_b128 v[222:225], v237 offset:36864
	ds_read_b128 v[226:229], v117 offset:32768
	ds_read_b128 v[230:233], v117 offset:36864
	v_mfma_f32_32x32x16_bf16 v[52:67], v[68:71], v[76:79], v[52:67]
	v_mfma_f32_32x32x16_bf16 v[36:51], v[72:75], v[76:79], v[36:51]
	v_mfma_f32_32x32x16_bf16 v[20:35], v[68:71], v[80:83], v[20:35]
	v_mfma_f32_32x32x16_bf16 v[4:19], v[72:75], v[80:83], v[4:19]
	v_mfma_f32_32x32x16_bf16 v[52:67], v[84:87], v[92:95], v[52:67]
	v_mfma_f32_32x32x16_bf16 v[36:51], v[88:91], v[92:95], v[36:51]
	v_mfma_f32_32x32x16_bf16 v[20:35], v[84:87], v[96:99], v[20:35]
	v_mfma_f32_32x32x16_bf16 v[4:19], v[88:91], v[96:99], v[4:19]
	v_mfma_f32_32x32x16_bf16 v[52:67], v[118:121], v[126:129], v[52:67]
	v_mfma_f32_32x32x16_bf16 v[36:51], v[122:125], v[126:129], v[36:51]
	v_mfma_f32_32x32x16_bf16 v[20:35], v[118:121], v[130:133], v[20:35]
	v_mfma_f32_32x32x16_bf16 v[4:19], v[122:125], v[130:133], v[4:19]
	v_mfma_f32_32x32x16_bf16 v[52:67], v[134:137], v[142:145], v[52:67]
	v_mfma_f32_32x32x16_bf16 v[36:51], v[138:141], v[142:145], v[36:51]
	v_mfma_f32_32x32x16_bf16 v[20:35], v[134:137], v[146:149], v[20:35]
	v_mfma_f32_32x32x16_bf16 v[4:19], v[138:141], v[146:149], v[4:19]
	s_waitcnt lgkmcnt(0)
	v_mfma_f32_32x32x16_bf16 v[52:67], v[150:153], v[158:161], v[52:67]
	v_mfma_f32_32x32x16_bf16 v[36:51], v[154:157], v[158:161], v[36:51]
	v_mfma_f32_32x32x16_bf16 v[20:35], v[150:153], v[162:165], v[20:35]
	v_mfma_f32_32x32x16_bf16 v[4:19], v[154:157], v[162:165], v[4:19]
	v_mfma_f32_32x32x16_bf16 v[52:67], v[168:171], v[176:179], v[52:67]
	v_mfma_f32_32x32x16_bf16 v[36:51], v[172:175], v[176:179], v[36:51]
	v_mfma_f32_32x32x16_bf16 v[20:35], v[168:171], v[180:183], v[20:35]
	v_mfma_f32_32x32x16_bf16 v[4:19], v[172:175], v[180:183], v[4:19]
	v_mfma_f32_32x32x16_bf16 v[52:67], v[184:187], v[192:195], v[52:67]
	v_mfma_f32_32x32x16_bf16 v[36:51], v[188:191], v[192:195], v[36:51]
	v_mfma_f32_32x32x16_bf16 v[20:35], v[184:187], v[198:201], v[20:35]
	v_mfma_f32_32x32x16_bf16 v[4:19], v[188:191], v[198:201], v[4:19]
	v_mfma_f32_32x32x16_bf16 v[52:67], v[218:221], v[226:229], v[52:67]
	v_mfma_f32_32x32x16_bf16 v[36:51], v[222:225], v[226:229], v[36:51]
	v_mfma_f32_32x32x16_bf16 v[20:35], v[218:221], v[230:233], v[20:35]
	v_mfma_f32_32x32x16_bf16 v[4:19], v[222:225], v[230:233], v[4:19]
	v_or_b32_e32 v68, s8, v113
	v_readlane_b32 s8, v252, 40
	s_add_i32 s6, s6, s8
	s_cmpk_gt_i32 s6, 0x7ff
	v_readlane_b32 s9, v252, 41
	v_mov_b32_e32 v88, s21
	v_mov_b32_e32 v89, s22
	v_mov_b32_e32 v90, s20
	v_add_u32_e32 v86, s7, v112
	v_min_i32_e32 v69, 0x8000, v86
	v_ashrrev_i32_e32 v69, 12, v69
	s_mov_b32 s7, 0x8000
	v_mul_hi_i32_i24_e32 v71, 0x6000, v69
	v_mul_i32_i24_e32 v70, 0x6000, v69
	v_cmp_gt_i32_e32 vcc, s7, v86
	v_add_u32_e32 v69, 0xffff8000, v86
	v_ashrrev_i32_e32 v72, 31, v86
	v_cndmask_b32_e32 v73, 0, v72, vcc
	v_cndmask_b32_e32 v72, v69, v86, vcc
	v_mov_b32_e32 v87, s23
	v_ashrrev_i32_e32 v69, 31, v68
	v_lshl_add_u64 v[70:71], s[2:3], 0, v[70:71]
	v_cndmask_b32_e32 v75, v87, v88, vcc
	v_cndmask_b32_e32 v74, v89, v90, vcc
	v_lshlrev_b64 v[72:73], 12, v[72:73]
	v_lshlrev_b64 v[68:69], 2, v[68:69]
	v_lshl_add_u64 v[72:73], v[74:75], 0, v[72:73]
	v_lshl_add_u64 v[84:85], v[72:73], 0, v[68:69]
	s_movk_i32 s7, 0x7fe0
	v_cmp_gt_i32_e32 vcc, s7, v86
	v_lshl_add_u64 v[82:83], v[70:71], 0, v[68:69]
	global_load_dwordx4 v[70:73], v[82:83], off
	global_load_dwordx4 v[74:77], v[84:85], off offset:16
	global_load_dwordx4 v[78:81], v[84:85], off
	s_waitcnt vmcnt(0)
;   template <int MF> DI void operator()(f32x16 (&acc)[MF][2], int mb, int nb, int l31, int h) const {
; #pragma unroll
;     for (int mi = 0; mi < MF; ++mi) {
;       const int row = mb + mi * 32 + l31;
;       const float* gr = gate + (size_t)modrow(row) * 6144;
;       const float* rp = row < TL ? res_lat + (size_t)row * D : res_ctx + (size_t)(row - TL) * D;
;       float* op = row < TL ? out_lat + (size_t)row * D : out_ctx + (size_t)(row - TL) * D;
; #pragma unroll
;       for (int g4 = 0; g4 < 4; ++g4)
; #pragma unroll
;         for (int ni = 0; ni < 2; ++ni) {
;           const int col0 = nb + 16 * g4 + 8 * h + 4 * ni;
;           const float4 gt = *(const float4*)(gr + col0);
;           const float4 rv = *(const float4*)(rp + col0);
;           *(float4*)(op + col0) = make_float4(rv.x + gt.x * acc[mi][ni][4 * g4], rv.y + gt.y * acc[mi][ni][4 * g4 + 1], rv.z + gt.z * acc[mi][ni][4 * g4 + 2], rv.w + gt.w * acc[mi][ni][4 * g4 + 3]);
;         }
;     }
;   }
	s_nop 9
	v_fma_f32 v52, v52, v70, v78
	v_fma_f32 v53, v53, v71, v79
	v_fma_f32 v54, v54, v72, v80
	v_fma_f32 v55, v55, v73, v81
	global_store_dwordx4 v[84:85], v[52:55], off
	global_load_dwordx4 v[52:55], v[82:83], off offset:16
	s_waitcnt vmcnt(0)
	s_nop 9
	v_fma_f32 v36, v36, v52, v74
	v_fma_f32 v37, v37, v53, v75
	v_fma_f32 v38, v38, v54, v76
	v_fma_f32 v39, v39, v55, v77
	global_store_dwordx4 v[84:85], v[36:39], off offset:16
	global_load_dwordx4 v[36:39], v[82:83], off offset:64
	s_nop 0
	global_load_dwordx4 v[52:55], v[84:85], off offset:80
	global_load_dwordx4 v[70:73], v[84:85], off offset:64
	s_waitcnt vmcnt(0)
	v_fma_f32 v36, v56, v36, v70
	v_fma_f32 v37, v57, v37, v71
	v_fma_f32 v38, v58, v38, v72
	v_fma_f32 v39, v59, v39, v73
	global_store_dwordx4 v[84:85], v[36:39], off offset:64
	global_load_dwordx4 v[36:39], v[82:83], off offset:80
	s_waitcnt vmcnt(0)
	v_fma_f32 v36, v40, v36, v52
	v_fma_f32 v37, v41, v37, v53
	v_fma_f32 v38, v42, v38, v54
	v_fma_f32 v39, v43, v39, v55
	global_store_dwordx4 v[84:85], v[36:39], off offset:80
	global_load_dwordx4 v[36:39], v[82:83], off offset:128
	s_nop 0
	global_load_dwordx4 v[40:43], v[84:85], off offset:144
	global_load_dwordx4 v[52:55], v[84:85], off offset:128
	s_waitcnt vmcnt(0)
	v_fma_f32 v36, v60, v36, v52
	v_fma_f32 v37, v61, v37, v53
	v_fma_f32 v38, v62, v38, v54
	v_fma_f32 v39, v63, v39, v55
	global_store_dwordx4 v[84:85], v[36:39], off offset:128
	global_load_dwordx4 v[36:39], v[82:83], off offset:144
	s_waitcnt vmcnt(0)
	v_pk_fma_f32 v[36:37], v[44:45], v[36:37], v[40:41]
	v_pk_fma_f32 v[38:39], v[46:47], v[38:39], v[42:43]
	global_store_dwordx4 v[84:85], v[36:39], off offset:144
	global_load_dwordx4 v[36:39], v[82:83], off offset:192
	s_nop 0
	global_load_dwordx4 v[40:43], v[84:85], off offset:208
	global_load_dwordx4 v[44:47], v[84:85], off offset:192
	s_waitcnt vmcnt(0)
	v_pk_fma_f32 v[36:37], v[64:65], v[36:37], v[44:45]
	v_pk_fma_f32 v[38:39], v[66:67], v[38:39], v[46:47]
	global_store_dwordx4 v[84:85], v[36:39], off offset:192
	global_load_dwordx4 v[36:39], v[82:83], off offset:208
	s_waitcnt vmcnt(0)
	v_pk_fma_f32 v[36:37], v[48:49], v[36:37], v[40:41]
	v_pk_fma_f32 v[38:39], v[50:51], v[38:39], v[42:43]
	v_or_b32_e32 v40, 32, v86
	global_store_dwordx4 v[84:85], v[36:39], off offset:208
	s_nop 1
	v_ashrrev_i32_e32 v36, 31, v40
	v_add_u32_e32 v38, 0xffff8020, v86
	v_cndmask_b32_e32 v37, 0, v36, vcc
	v_cndmask_b32_e32 v36, v38, v40, vcc
	v_cndmask_b32_e32 v39, v87, v88, vcc
	v_cndmask_b32_e32 v38, v89, v90, vcc
	v_lshlrev_b64 v[36:37], 12, v[36:37]
	v_lshl_add_u64 v[36:37], v[38:39], 0, v[36:37]
	v_min_i32_e32 v38, 0x8000, v40
	v_ashrrev_i32_e32 v38, 12, v38
	v_mul_hi_i32_i24_e32 v39, 0x6000, v38
	v_mul_i32_i24_e32 v38, 0x6000, v38
	v_lshl_add_u64 v[38:39], s[2:3], 0, v[38:39]
	v_lshl_add_u64 v[48:49], v[38:39], 0, v[68:69]
	v_lshl_add_u64 v[50:51], v[36:37], 0, v[68:69]
	global_load_dwordx4 v[36:39], v[48:49], off
	global_load_dwordx4 v[40:43], v[50:51], off offset:16
	global_load_dwordx4 v[44:47], v[50:51], off
	s_waitcnt vmcnt(0)
	v_pk_fma_f32 v[20:21], v[20:21], v[36:37], v[44:45]
	v_pk_fma_f32 v[22:23], v[22:23], v[38:39], v[46:47]
	global_store_dwordx4 v[50:51], v[20:23], off
	global_load_dwordx4 v[20:23], v[48:49], off offset:16
	s_waitcnt vmcnt(0)
	v_pk_fma_f32 v[4:5], v[4:5], v[20:21], v[40:41]
	v_pk_fma_f32 v[6:7], v[6:7], v[22:23], v[42:43]
	global_store_dwordx4 v[50:51], v[4:7], off offset:16
	global_load_dwordx4 v[4:7], v[48:49], off offset:64
	s_nop 0
	global_load_dwordx4 v[20:23], v[50:51], off offset:80
	global_load_dwordx4 v[36:39], v[50:51], off offset:64
	s_waitcnt vmcnt(0)
	v_pk_fma_f32 v[4:5], v[24:25], v[4:5], v[36:37]
	v_pk_fma_f32 v[6:7], v[26:27], v[6:7], v[38:39]
	global_store_dwordx4 v[50:51], v[4:7], off offset:64
	global_load_dwordx4 v[4:7], v[48:49], off offset:80
	s_waitcnt vmcnt(0)
	v_pk_fma_f32 v[4:5], v[8:9], v[4:5], v[20:21]
	v_pk_fma_f32 v[6:7], v[10:11], v[6:7], v[22:23]
	global_store_dwordx4 v[50:51], v[4:7], off offset:80
	global_load_dwordx4 v[4:7], v[48:49], off offset:128
	s_nop 0
	global_load_dwordx4 v[8:11], v[50:51], off offset:144
	global_load_dwordx4 v[20:23], v[50:51], off offset:128
	s_waitcnt vmcnt(0)
	v_pk_fma_f32 v[4:5], v[28:29], v[4:5], v[20:21]
	v_pk_fma_f32 v[6:7], v[30:31], v[6:7], v[22:23]
	global_store_dwordx4 v[50:51], v[4:7], off offset:128
	global_load_dwordx4 v[4:7], v[48:49], off offset:144
	s_waitcnt vmcnt(0)
	v_pk_fma_f32 v[4:5], v[12:13], v[4:5], v[8:9]
	v_pk_fma_f32 v[6:7], v[14:15], v[6:7], v[10:11]
	global_store_dwordx4 v[50:51], v[4:7], off offset:144
	global_load_dwordx4 v[4:7], v[48:49], off offset:192
	s_nop 0
	global_load_dwordx4 v[8:11], v[50:51], off offset:208
	global_load_dwordx4 v[12:15], v[50:51], off offset:192
	s_waitcnt vmcnt(0)
	v_pk_fma_f32 v[4:5], v[32:33], v[4:5], v[12:13]
	v_pk_fma_f32 v[6:7], v[34:35], v[6:7], v[14:15]
	global_store_dwordx4 v[50:51], v[4:7], off offset:192
	global_load_dwordx4 v[4:7], v[48:49], off offset:208
	s_waitcnt vmcnt(0)
	v_pk_fma_f32 v[4:5], v[16:17], v[4:5], v[8:9]
	v_pk_fma_f32 v[6:7], v[18:19], v[6:7], v[10:11]
	global_store_dwordx4 v[50:51], v[4:7], off offset:208
	s_cbranch_scc0 .LBB0_34

; __device__ __forceinline__ size_t wofs(int layer) { return (layer & 1) ? W2_DELTA : (size_t)0; }
; DI int tid_l() { int t = threadIdx.x; asm volatile("" : "+v"(t)); return t; }
; DI int bid_l() { int t = blockIdx.x; asm volatile("" : "+s"(t)); return t; }
; template <int MF, int BK, class Epi>
; DI void gemm_phase_t(char* lds, const GemmDesc g, const Epi epi) {
;   constexpr int BM = MF * 64, LS = BK + 8, CPR = BK / 8, RSTEP = 256 / CPR;
;   constexpr int APT = BM * CPR / 256, BPT = 128 * CPR / 256, STG = (BM + 128) * LS, NKK = BK / 16;
;   u16* sbase = (u16*)lds;
;   const int tid = tid_l(), lane = tid & 63, w = tid >> 6, wm = w >> 1, wn = w & 1, l31 = lane & 31, h = lane >> 5;
;   const int ntn = g.Npad / 128, ntm = g.M / BM, ntiles = ntm * ntn, nk = g.K / BK;
;   const int lr = tid / CPR, lc = tid % CPR;
;   for (int t = bid_l(); t < ntiles; t += gridDim.x) {
;     const int tn = t % ntn, tm = t / ntn;
;     const int m0 = tm * BM, n0 = tn * 128;
;     const u16* Ap = g.A + (size_t)(m0 + lr) * g.lda + lc * 8;
;     const u16* Bp = g.Bt + (size_t)(n0 + lr) * g.ldb + lc * 8;
; DI void run_phase(const Params& p, char* lds, int ph) {
;     ...
;     case 7: if (en(13)) {
;       const u16* Amix = (const u16*)(ws + (even ? OFF_MIXE : OFF_MIXO));
;       const EpiResid ep{res_lat, res_ctx, p.out, (float*)(ws + OFF_HCTX), modl + 2 * 1024};
;       GemmDesc g{Amix, 1024, (const u16*)(ws + wofs(layer) + OFF_WOUT), 1024, TL, 1024, 1024};
;       gemm_phase(lds, g, ep);
.LBB0_301:
	v_readlane_b32 s2, v253, 38
	s_cmp_gt_i32 s2, 5
	s_mov_b64 s[0:1], -1
	s_cbranch_scc0 .LBB0_341
	v_writelane_b32 v253, s50, 48
	s_cmp_gt_i32 s2, 6
	s_nop 0
	v_writelane_b32 v253, s51, 49
	v_writelane_b32 v253, s28, 42
	s_nop 1
	v_writelane_b32 v253, s29, 43
	v_writelane_b32 v253, s30, 44
	v_writelane_b32 v253, s31, 45
	s_cbranch_scc0 .LBB0_314
	s_and_b64 s[0:1], s[20:21], exec
	s_mov_b32 s0, 0xe1ac000
	s_cselect_b32 s48, s0, 0x7bac000
	s_add_u32 s2, s30, s48
	s_addc_u32 s3, s31, 0
	v_readlane_b32 s0, v253, 36
	v_readlane_b32 s1, v253, 37
	s_add_u32 s0, s0, 0x2000
	s_addc_u32 s1, s1, 0
	s_and_b64 s[4:5], s[20:21], exec
	s_cselect_b32 s6, 0, 0x1c364000
	s_add_u32 s4, s30, s6
	s_addc_u32 s5, s31, 0
	s_add_u32 s4, s4, 0x144c000
	s_addc_u32 s5, s5, 0
	v_mov_b32_e32 v4, v0
	v_readlane_b32 s8, v251, 0
	s_cmpk_gt_i32 s8, 0x7ff
	s_cbranch_scc1 .LBB0_308
	v_ashrrev_i32_e32 v2, 31, v4
	v_lshrrev_b32_e32 v2, 29, v2
	v_add_u32_e32 v5, v4, v2
	v_ashrrev_i32_e32 v2, 3, v5
	v_and_b32_e32 v5, -8, v5
	v_sub_u32_e32 v5, v4, v5
	v_bfe_u32 v8, v4, 5, 1
	v_and_b32_e32 v9, 31, v4
	v_and_b32_e32 v10, 64, v4
	v_lshlrev_b32_e32 v6, 3, v5
	v_lshlrev_b32_e32 v112, 4, v5
	v_and_b32_e32 v5, 0x5f, v4
	v_ashrrev_i32_e32 v4, 1, v4
	s_movk_i32 s9, 0xffc0
	v_and_or_b32 v113, v4, s9, v9
	s_movk_i32 s9, 0x90
	v_ashrrev_i32_e32 v7, 31, v6
	v_mul_lo_u32 v115, v2, s9
	s_mov_b32 s7, s49
	v_lshlrev_b64 v[6:7], 1, v[6:7]
	v_lshlrev_b32_e32 v11, 4, v8
	v_lshl_or_b32 v114, v8, 3, v10
	v_add_u32_e32 v4, 0x3600, v115
	v_mul_lo_u32 v8, v113, s9
	v_mul_u32_u24_e32 v5, 0x90, v5
	v_lshl_add_u64 v[100:101], s[2:3], 0, v[6:7]
	v_lshl_add_u64 v[102:103], s[4:5], 0, v[6:7]
	v_lshl_add_u64 v[104:105], s[6:7], 0, v[6:7]
	v_lshl_add_u64 v[106:107], s[48:49], 0, v[6:7]
	v_add_u32_e32 v116, v112, v4
	v_add_u32_e32 v117, v11, v5
	v_add_u32_e32 v118, v11, v8
	v_bfe_u32 v4, v0, 1, 3
	v_bfe_u32 v5, v0, 5, 1
	v_xor_b32_e32 v4, v4, v5
	v_lshlrev_b32_e32 v4, 4, v4
	v_add_u32_e32 v4, 0x100, v4
	v_and_b32_e32 v5, 31, v0
	v_bfe_u32 v6, v0, 7, 1
	v_lshl_or_b32 v6, v6, 6, v5
	v_lshl_add_u32 v238, v6, 7, v4
	v_bfe_u32 v6, v0, 6, 1
	v_lshl_or_b32 v6, v6, 6, v5
	v_lshl_add_u32 v234, v6, 7, v4
	v_add_u32_e32 v234, 0x4000, v234
	v_xor_b32_e32 v239, 0x20, v238
	v_xor_b32_e32 v235, 0x20, v234
	v_xor_b32_e32 v240, 0x40, v238
	v_xor_b32_e32 v236, 0x40, v234
	v_xor_b32_e32 v241, 0x60, v238
	v_xor_b32_e32 v237, 0x60, v234
	v_bfe_u32 v4, v0, 4, 3
	v_and_b32_e32 v5, 7, v0
	v_xor_b32_e32 v4, v4, v5
	v_lshlrev_b32_e32 v4, 4, v4
	v_bfe_u32 v5, v0, 3, 3
	s_movk_i32 s9, 0x800
	v_mad_u32_u24 v108, v5, s9, v4
	v_add_u32_e32 v109, 0x10000, v108
	v_add_u32_e32 v110, 0x20000, v108
	v_add_u32_e32 v111, 0x30000, v108
	v_lshrrev_b32_e32 v5, 6, v0
	v_lshlrev_b32_e32 v5, 10, v5
	v_add_u32_e32 v5, 0x100, v5
	s_nop 0
	v_readfirstlane_b32 s100, v5

; template <int MF, int BK, class Epi>
; DI void gemm_phase_t(char* lds, const GemmDesc g, const Epi epi) {
;     ...
;   for (int t = bid_l(); t < ntiles; t += gridDim.x) {
;     const int tn = t % ntn, tm = t / ntn;
;     const int m0 = tm * BM, n0 = tn * 128;
;     const u16* Ap = g.A + (size_t)(m0 + lr) * g.lda + lc * 8;
;     const u16* Bp = g.Bt + (size_t)(n0 + lr) * g.ldb + lc * 8;
;     u32x4 ra[APT], rb[BPT];
; #pragma unroll
;     for (int j = 0; j < APT; ++j) ra[j] = *(const u32x4*)(Ap + (size_t)j * RSTEP * g.lda);
; #pragma unroll
;     for (int j = 0; j < BPT; ++j) rb[j] = *(const u32x4*)(Bp + (size_t)j * RSTEP * g.ldb);
; #pragma unroll
;     for (int j = 0; j < APT; ++j) *(u32x4*)(sbase + (lr + RSTEP * j) * LS + lc * 8) = ra[j];
; #pragma unroll
;     for (int j = 0; j < BPT; ++j) *(u32x4*)(sbase + BM * LS + (lr + RSTEP * j) * LS + lc * 8) = rb[j];
;     if (nk > 1) {
; #pragma unroll
;       for (int j = 0; j < APT; ++j) ra[j] = *(const u32x4*)(Ap + (size_t)j * RSTEP * g.lda + BK);
; #pragma unroll
;       for (int j = 0; j < BPT; ++j) rb[j] = *(const u32x4*)(Bp + (size_t)j * RSTEP * g.ldb + BK);
;     }
;     f32x16 acc[MF][2];
; #pragma unroll
;     for (int i = 0; i < MF; ++i)
; #pragma unroll
;       for (int j = 0; j < 2; ++j) acc[i][j] = zero16();
;     for (int kt = 0; kt < nk; ++kt) {
;       __syncthreads();
;       const u16* sA = sbase + (kt & 1) * STG;
;       const u16* sB = sA + BM * LS;
;       if (kt + 1 < nk) {
;         u16* nA = sbase + ((kt + 1) & 1) * STG;
; #pragma unroll
;         for (int j = 0; j < APT; ++j) *(u32x4*)(nA + (lr + RSTEP * j) * LS + lc * 8) = ra[j];
; #pragma unroll
;         for (int j = 0; j < BPT; ++j) *(u32x4*)(nA + BM * LS + (lr + RSTEP * j) * LS + lc * 8) = rb[j];
;         if (kt + 2 < nk) {
; #pragma unroll
;           for (int j = 0; j < APT; ++j) ra[j] = *(const u32x4*)(Ap + (size_t)j * RSTEP * g.lda + (kt + 2) * BK);
; #pragma unroll
;           for (int j = 0; j < BPT; ++j) rb[j] = *(const u32x4*)(Bp + (size_t)j * RSTEP * g.ldb + (kt + 2) * BK);
;         }
;       }
;       bf16x8 af[NKK][MF], bfr[NKK][2];
; #pragma unroll
;       for (int kk = 0; kk < NKK; ++kk) {
; #pragma unroll
;         for (int ni = 0; ni < 2; ++ni) bfr[kk][ni] = *(const bf16x8*)(sB + (wn * 64 + ni * 32 + l31) * LS + kk * 16 + h * 8);
; #pragma unroll
.Lnomap_tl2:
	s_ashr_i32 s6, s98, 31
	s_lshr_b32 s6, s6, 29
	s_add_i32 s6, s98, s6
	s_and_b32 s7, s6, 0x1fffff8
	s_lshl_b32 s6, s6, 4
	s_and_b32 s6, s6, 0xffffff80
	v_add_u32_e32 v4, s6, v2
	v_ashrrev_i32_e32 v5, 31, v4
	v_lshlrev_b64 v[36:37], 11, v[4:5]
	v_lshl_add_u64 v[38:39], v[100:101], 0, v[36:37]
	s_sub_i32 s7, s98, s7
	s_lshl_b32 s7, s7, 7
	v_add_u32_e32 v20, s7, v2
	v_ashrrev_i32_e32 v21, 31, v20
	v_lshlrev_b64 v[46:47], 11, v[20:21]
	v_lshl_add_u64 v[48:49], v[102:103], 0, v[46:47]
	v_mov_b32_e32 v60, 0
	v_readfirstlane_b32 s12, v38
	v_readfirstlane_b32 s13, v39
	v_readfirstlane_b32 s14, v48
	v_readfirstlane_b32 s15, v49
	v_mov_b32_e32 v4, 0
	v_mov_b32_e32 v5, 0
	v_mov_b32_e32 v6, 0
	v_mov_b32_e32 v7, 0
	v_mov_b32_e32 v8, 0
	v_mov_b32_e32 v9, 0
	v_mov_b32_e32 v10, 0
	v_mov_b32_e32 v11, 0
	v_mov_b32_e32 v12, 0
	v_mov_b32_e32 v13, 0
	v_mov_b32_e32 v14, 0
	v_mov_b32_e32 v15, 0
	v_mov_b32_e32 v16, 0
	v_mov_b32_e32 v17, 0
	v_mov_b32_e32 v18, 0
	v_mov_b32_e32 v19, 0
	v_mov_b32_e32 v20, 0
	v_mov_b32_e32 v21, 0
	v_mov_b32_e32 v22, 0
	v_mov_b32_e32 v23, 0
	v_mov_b32_e32 v24, 0
	v_mov_b32_e32 v25, 0
	v_mov_b32_e32 v26, 0
	v_mov_b32_e32 v27, 0
	v_mov_b32_e32 v28, 0
	v_mov_b32_e32 v29, 0
	v_mov_b32_e32 v30, 0
	v_mov_b32_e32 v31, 0
	v_mov_b32_e32 v32, 0
	v_mov_b32_e32 v33, 0
	v_mov_b32_e32 v34, 0
	v_mov_b32_e32 v35, 0
	v_mov_b32_e32 v36, 0
	v_mov_b32_e32 v37, 0
	v_mov_b32_e32 v38, 0
	v_mov_b32_e32 v39, 0
	v_mov_b32_e32 v40, 0
	v_mov_b32_e32 v41, 0
	v_mov_b32_e32 v42, 0
	v_mov_b32_e32 v43, 0
	v_mov_b32_e32 v44, 0
	v_mov_b32_e32 v45, 0
	v_mov_b32_e32 v46, 0
	v_mov_b32_e32 v47, 0
	v_mov_b32_e32 v48, 0
	v_mov_b32_e32 v49, 0
	v_mov_b32_e32 v50, 0
	v_mov_b32_e32 v51, 0
	v_mov_b32_e32 v52, 0
	v_mov_b32_e32 v53, 0
	v_mov_b32_e32 v54, 0
	v_mov_b32_e32 v55, 0
	v_mov_b32_e32 v56, 0
	v_mov_b32_e32 v57, 0
	v_mov_b32_e32 v58, 0
	v_mov_b32_e32 v59, 0
	v_mov_b32_e32 v60, 0
	v_mov_b32_e32 v61, 0
	v_mov_b32_e32 v62, 0
	v_mov_b32_e32 v63, 0
	v_mov_b32_e32 v64, 0
	v_mov_b32_e32 v65, 0
	v_mov_b32_e32 v66, 0
	v_mov_b32_e32 v67, 0
	s_add_i32 m0, s100, 0x0
	s_nop 0
	global_load_lds_dwordx4 v108, s[12:13]
	s_add_i32 m0, s100, 0x1000
	s_nop 0
	global_load_lds_dwordx4 v109, s[12:13]
	s_add_i32 m0, s100, 0x2000
	s_nop 0
	global_load_lds_dwordx4 v110, s[12:13]
	s_add_i32 m0, s100, 0x3000
	s_nop 0
	global_load_lds_dwordx4 v111, s[12:13]
	s_add_i32 m0, s100, 0x4000
	s_nop 0
	global_load_lds_dwordx4 v108, s[14:15]
	s_add_i32 m0, s100, 0x5000
	s_nop 0
	global_load_lds_dwordx4 v109, s[14:15]
	s_add_i32 m0, s100, 0x6000
	s_nop 0
	global_load_lds_dwordx4 v110, s[14:15]
	s_add_i32 m0, s100, 0x7000
	s_nop 0
	global_load_lds_dwordx4 v111, s[14:15]
	s_add_u32 s12, s12, 0x80
	s_addc_u32 s13, s13, 0
	s_add_u32 s14, s14, 0x80
	s_addc_u32 s15, s15, 0
	s_waitcnt vmcnt(0)
	s_waitcnt lgkmcnt(0)
	s_barrier
	s_add_i32 m0, s100, 0x8000
	s_nop 0
	global_load_lds_dwordx4 v108, s[12:13]
	s_add_i32 m0, s100, 0x9000
	s_nop 0
	global_load_lds_dwordx4 v109, s[12:13]
	s_add_i32 m0, s100, 0xa000
	s_nop 0
	global_load_lds_dwordx4 v110, s[12:13]
	s_add_i32 m0, s100, 0xb000
	s_nop 0
	global_load_lds_dwordx4 v111, s[12:13]
	s_add_i32 m0, s100, 0xc000
	s_nop 0
	global_load_lds_dwordx4 v108, s[14:15]
	s_add_i32 m0, s100, 0xd000
	s_nop 0
	global_load_lds_dwordx4 v109, s[14:15]
	s_add_i32 m0, s100, 0xe000
	s_nop 0
	global_load_lds_dwordx4 v110, s[14:15]
	s_add_i32 m0, s100, 0xf000
	s_nop 0
	global_load_lds_dwordx4 v111, s[14:15]
	s_add_u32 s12, s12, 0x80
	s_addc_u32 s13, s13, 0
	s_add_u32 s14, s14, 0x80
	s_addc_u32 s15, s15, 0
	ds_read_b128 v[68:71], v234
	ds_read_b128 v[72:75], v234 offset:4096
	ds_read_b128 v[76:79], v238
	ds_read_b128 v[80:83], v238 offset:4096
	ds_read_b128 v[84:87], v235
	ds_read_b128 v[88:91], v235 offset:4096
	ds_read_b128 v[92:95], v239
	ds_read_b128 v[96:99], v239 offset:4096
	ds_read_b128 v[118:121], v236
	ds_read_b128 v[122:125], v236 offset:4096
	ds_read_b128 v[126:129], v240
	ds_read_b128 v[130:133], v240 offset:4096
	ds_read_b128 v[134:137], v237
	ds_read_b128 v[138:141], v237 offset:4096
	ds_read_b128 v[142:145], v241
	ds_read_b128 v[146:149], v241 offset:4096
	s_movk_i32 s9, 7
.Ldma_op_loop:
	s_waitcnt vmcnt(0)
	s_waitcnt lgkmcnt(0)
	s_barrier
	s_add_i32 m0, s100, 0x0
	s_nop 0
	global_load_lds_dwordx4 v108, s[12:13]
	s_add_i32 m0, s100, 0x1000
	s_nop 0
	global_load_lds_dwordx4 v109, s[12:13]
	s_add_i32 m0, s100, 0x2000
	s_nop 0
	global_load_lds_dwordx4 v110, s[12:13]
	s_add_i32 m0, s100, 0x3000
	s_nop 0
	global_load_lds_dwordx4 v111, s[12:13]
	s_add_i32 m0, s100, 0x4000
	s_nop 0
	global_load_lds_dwordx4 v108, s[14:15]
	s_add_i32 m0, s100, 0x5000
	s_nop 0
	global_load_lds_dwordx4 v109, s[14:15]
	s_add_i32 m0, s100, 0x6000
	s_nop 0
	global_load_lds_dwordx4 v110, s[14:15]
	s_add_i32 m0, s100, 0x7000
	s_nop 0
	global_load_lds_dwordx4 v111, s[14:15]
	s_add_u32 s12, s12, 0x80
	s_addc_u32 s13, s13, 0
	s_add_u32 s14, s14, 0x80
	s_addc_u32 s15, s15, 0
	ds_read_b128 v[150:153], v234 offset:32768
	ds_read_b128 v[154:157], v234 offset:36864
	ds_read_b128 v[158:161], v238 offset:32768
	ds_read_b128 v[162:165], v238 offset:36864
	ds_read_b128 v[168:171], v235 offset:32768
	ds_read_b128 v[172:175], v235 offset:36864
	ds_read_b128 v[176:179], v239 offset:32768
	ds_read_b128 v[180:183], v239 offset:36864
	ds_read_b128 v[184:187], v236 offset:32768
	ds_read_b128 v[188:191], v236 offset:36864
	ds_read_b128 v[192:195], v240 offset:32768
	ds_read_b128 v[198:201], v240 offset:36864
	ds_read_b128 v[218:221], v237 offset:32768
	ds_read_b128 v[222:225], v237 offset:36864
	ds_read_b128 v[226:229], v241 offset:32768
	ds_read_b128 v[230:233], v241 offset:36864
	v_mfma_f32_32x32x16_bf16 v[52:67], v[68:71], v[76:79], v[52:67]
	v_mfma_f32_32x32x16_bf16 v[36:51], v[72:75], v[76:79], v[36:51]
	v_mfma_f32_32x32x16_bf16 v[20:35], v[68:71], v[80:83], v[20:35]
	v_mfma_f32_32x32x16_bf16 v[4:19], v[72:75], v[80:83], v[4:19]
	v_mfma_f32_32x32x16_bf16 v[52:67], v[84:87], v[92:95], v[52:67]
	v_mfma_f32_32x32x16_bf16 v[36:51], v[88:91], v[92:95], v[36:51]
	v_mfma_f32_32x32x16_bf16 v[20:35], v[84:87], v[96:99], v[20:35]
	v_mfma_f32_32x32x16_bf16 v[4:19], v[88:91], v[96:99], v[4:19]
	v_mfma_f32_32x32x16_bf16 v[52:67], v[118:121], v[126:129], v[52:67]
	v_mfma_f32_32x32x16_bf16 v[36:51], v[122:125], v[126:129], v[36:51]
	v_mfma_f32_32x32x16_bf16 v[20:35], v[118:121], v[130:133], v[20:35]
	v_mfma_f32_32x32x16_bf16 v[4:19], v[122:125], v[130:133], v[4:19]
	v_mfma_f32_32x32x16_bf16 v[52:67], v[134:137], v[142:145], v[52:67]
	v_mfma_f32_32x32x16_bf16 v[36:51], v[138:141], v[142:145], v[36:51]
	v_mfma_f32_32x32x16_bf16 v[20:35], v[134:137], v[146:149], v[20:35]
	v_mfma_f32_32x32x16_bf16 v[4:19], v[138:141], v[146:149], v[4:19]
	s_waitcnt vmcnt(0)
	s_waitcnt lgkmcnt(0)
	s_barrier
; template <int MF, int BK, class Epi>
; DI void gemm_phase_t(char* lds, const GemmDesc g, const Epi epi) {
;     ...
;     for (int kt = 0; kt < nk; ++kt) {
;       __syncthreads();
;       const u16* sA = sbase + (kt & 1) * STG;
;       const u16* sB = sA + BM * LS;
;       if (kt + 1 < nk) {
;         u16* nA = sbase + ((kt + 1) & 1) * STG;
; #pragma unroll
;         for (int j = 0; j < APT; ++j) *(u32x4*)(nA + (lr + RSTEP * j) * LS + lc * 8) = ra[j];
; #pragma unroll
;         for (int j = 0; j < BPT; ++j) *(u32x4*)(nA + BM * LS + (lr + RSTEP * j) * LS + lc * 8) = rb[j];
;         if (kt + 2 < nk) {
; #pragma unroll
;           for (int j = 0; j < APT; ++j) ra[j] = *(const u32x4*)(Ap + (size_t)j * RSTEP * g.lda + (kt + 2) * BK);
; #pragma unroll
;           for (int j = 0; j < BPT; ++j) rb[j] = *(const u32x4*)(Bp + (size_t)j * RSTEP * g.ldb + (kt + 2) * BK);
;         }
;       }
;       bf16x8 af[NKK][MF], bfr[NKK][2];
; #pragma unroll
;       for (int kk = 0; kk < NKK; ++kk) {
; #pragma unroll
;         for (int ni = 0; ni < 2; ++ni) bfr[kk][ni] = *(const bf16x8*)(sB + (wn * 64 + ni * 32 + l31) * LS + kk * 16 + h * 8);
; #pragma unroll
;         for (int mi = 0; mi < MF; ++mi) af[kk][mi] = *(const bf16x8*)(sA + (wm * (MF * 32) + mi * 32 + l31) * LS + kk * 16 + h * 8);
;       }
;       __builtin_amdgcn_sched_barrier(0);
; #pragma unroll
;       for (int kk = 0; kk < NKK; ++kk)
; #pragma unroll
;         for (int mi = 0; mi < MF; ++mi)
; #pragma unroll
;           for (int ni = 0; ni < 2; ++ni) acc[mi][ni] = MFMA32(bfr[kk][ni], af[kk][mi], acc[mi][ni]);
;   template <int MF> DI void operator()(f32x16 (&acc)[MF][2], int mb, int nb, int l31, int h) const {
; #pragma unroll
;     for (int mi = 0; mi < MF; ++mi) {
;       const int row = mb + mi * 32 + l31;
;       const float* gr = gate + (size_t)modrow(row) * 6144;
;       const float* rp = row < TL ? res_lat + (size_t)row * D : res_ctx + (size_t)(row - TL) * D;
;       float* op = row < TL ? out_lat + (size_t)row * D : out_ctx + (size_t)(row - TL) * D;
; #pragma unroll
;       for (int g4 = 0; g4 < 4; ++g4)
; #pragma unroll
;         for (int ni = 0; ni < 2; ++ni) {
;           const int col0 = nb + 16 * g4 + 8 * h + 4 * ni;
;           const float4 gt = *(const float4*)(gr + col0);
;           const float4 rv = *(const float4*)(rp + col0);
	s_add_i32 m0, s100, 0x8000
	s_nop 0
	global_load_lds_dwordx4 v108, s[12:13]
	s_add_i32 m0, s100, 0x9000
	s_nop 0
	global_load_lds_dwordx4 v109, s[12:13]
	s_add_i32 m0, s100, 0xa000
	s_nop 0
	global_load_lds_dwordx4 v110, s[12:13]
	s_add_i32 m0, s100, 0xb000
	s_nop 0
	global_load_lds_dwordx4 v111, s[12:13]
	s_add_i32 m0, s100, 0xc000
	s_nop 0
	global_load_lds_dwordx4 v108, s[14:15]
	s_add_i32 m0, s100, 0xd000
	s_nop 0
	global_load_lds_dwordx4 v109, s[14:15]
	s_add_i32 m0, s100, 0xe000
	s_nop 0
	global_load_lds_dwordx4 v110, s[14:15]
	s_add_i32 m0, s100, 0xf000
	s_nop 0
	global_load_lds_dwordx4 v111, s[14:15]
	s_add_u32 s12, s12, 0x80
	s_addc_u32 s13, s13, 0
	s_add_u32 s14, s14, 0x80
	s_addc_u32 s15, s15, 0
	ds_read_b128 v[68:71], v234
	ds_read_b128 v[72:75], v234 offset:4096
	ds_read_b128 v[76:79], v238
	ds_read_b128 v[80:83], v238 offset:4096
	ds_read_b128 v[84:87], v235
	ds_read_b128 v[88:91], v235 offset:4096
	ds_read_b128 v[92:95], v239
	ds_read_b128 v[96:99], v239 offset:4096
	ds_read_b128 v[118:121], v236
	ds_read_b128 v[122:125], v236 offset:4096
	ds_read_b128 v[126:129], v240
	ds_read_b128 v[130:133], v240 offset:4096
	ds_read_b128 v[134:137], v237
	ds_read_b128 v[138:141], v237 offset:4096
	ds_read_b128 v[142:145], v241
	ds_read_b128 v[146:149], v241 offset:4096
	v_mfma_f32_32x32x16_bf16 v[52:67], v[150:153], v[158:161], v[52:67]
	v_mfma_f32_32x32x16_bf16 v[36:51], v[154:157], v[158:161], v[36:51]
	v_mfma_f32_32x32x16_bf16 v[20:35], v[150:153], v[162:165], v[20:35]
	v_mfma_f32_32x32x16_bf16 v[4:19], v[154:157], v[162:165], v[4:19]
	v_mfma_f32_32x32x16_bf16 v[52:67], v[168:171], v[176:179], v[52:67]
	v_mfma_f32_32x32x16_bf16 v[36:51], v[172:175], v[176:179], v[36:51]
	v_mfma_f32_32x32x16_bf16 v[20:35], v[168:171], v[180:183], v[20:35]
	v_mfma_f32_32x32x16_bf16 v[4:19], v[172:175], v[180:183], v[4:19]
	v_mfma_f32_32x32x16_bf16 v[52:67], v[184:187], v[192:195], v[52:67]
	v_mfma_f32_32x32x16_bf16 v[36:51], v[188:191], v[192:195], v[36:51]
	v_mfma_f32_32x32x16_bf16 v[20:35], v[184:187], v[198:201], v[20:35]
	v_mfma_f32_32x32x16_bf16 v[4:19], v[188:191], v[198:201], v[4:19]
	v_mfma_f32_32x32x16_bf16 v[52:67], v[218:221], v[226:229], v[52:67]
	v_mfma_f32_32x32x16_bf16 v[36:51], v[222:225], v[226:229], v[36:51]
	v_mfma_f32_32x32x16_bf16 v[20:35], v[218:221], v[230:233], v[20:35]
	v_mfma_f32_32x32x16_bf16 v[4:19], v[222:225], v[230:233], v[4:19]
	s_add_i32 s9, s9, -1
	s_cmp_lg_u32 s9, 0
	s_cbranch_scc1 .Ldma_op_loop
	s_waitcnt vmcnt(0)
	s_waitcnt lgkmcnt(0)
	s_barrier
	ds_read_b128 v[150:153], v234 offset:32768
	ds_read_b128 v[154:157], v234 offset:36864
	ds_read_b128 v[158:161], v238 offset:32768
	ds_read_b128 v[162:165], v238 offset:36864
	ds_read_b128 v[168:171], v235 offset:32768
	ds_read_b128 v[172:175], v235 offset:36864
	ds_read_b128 v[176:179], v239 offset:32768
	ds_read_b128 v[180:183], v239 offset:36864
	ds_read_b128 v[184:187], v236 offset:32768
	ds_read_b128 v[188:191], v236 offset:36864
	ds_read_b128 v[192:195], v240 offset:32768
	ds_read_b128 v[198:201], v240 offset:36864
	ds_read_b128 v[218:221], v237 offset:32768
	ds_read_b128 v[222:225], v237 offset:36864
	ds_read_b128 v[226:229], v241 offset:32768
	ds_read_b128 v[230:233], v241 offset:36864
	v_mfma_f32_32x32x16_bf16 v[52:67], v[68:71], v[76:79], v[52:67]
	v_mfma_f32_32x32x16_bf16 v[36:51], v[72:75], v[76:79], v[36:51]
	v_mfma_f32_32x32x16_bf16 v[20:35], v[68:71], v[80:83], v[20:35]
	v_mfma_f32_32x32x16_bf16 v[4:19], v[72:75], v[80:83], v[4:19]
	v_mfma_f32_32x32x16_bf16 v[52:67], v[84:87], v[92:95], v[52:67]
	v_mfma_f32_32x32x16_bf16 v[36:51], v[88:91], v[92:95], v[36:51]
	v_mfma_f32_32x32x16_bf16 v[20:35], v[84:87], v[96:99], v[20:35]
	v_mfma_f32_32x32x16_bf16 v[4:19], v[88:91], v[96:99], v[4:19]
	v_mfma_f32_32x32x16_bf16 v[52:67], v[118:121], v[126:129], v[52:67]
	v_mfma_f32_32x32x16_bf16 v[36:51], v[122:125], v[126:129], v[36:51]
	v_mfma_f32_32x32x16_bf16 v[20:35], v[118:121], v[130:133], v[20:35]
	v_mfma_f32_32x32x16_bf16 v[4:19], v[122:125], v[130:133], v[4:19]
	v_mfma_f32_32x32x16_bf16 v[52:67], v[134:137], v[142:145], v[52:67]
	v_mfma_f32_32x32x16_bf16 v[36:51], v[138:141], v[142:145], v[36:51]
	v_mfma_f32_32x32x16_bf16 v[20:35], v[134:137], v[146:149], v[20:35]
	v_mfma_f32_32x32x16_bf16 v[4:19], v[138:141], v[146:149], v[4:19]
	s_waitcnt lgkmcnt(0)
	v_mfma_f32_32x32x16_bf16 v[52:67], v[150:153], v[158:161], v[52:67]
	v_mfma_f32_32x32x16_bf16 v[36:51], v[154:157], v[158:161], v[36:51]
	v_mfma_f32_32x32x16_bf16 v[20:35], v[150:153], v[162:165], v[20:35]
	v_mfma_f32_32x32x16_bf16 v[4:19], v[154:157], v[162:165], v[4:19]
	v_mfma_f32_32x32x16_bf16 v[52:67], v[168:171], v[176:179], v[52:67]
	v_mfma_f32_32x32x16_bf16 v[36:51], v[172:175], v[176:179], v[36:51]
	v_mfma_f32_32x32x16_bf16 v[20:35], v[168:171], v[180:183], v[20:35]
	v_mfma_f32_32x32x16_bf16 v[4:19], v[172:175], v[180:183], v[4:19]
	v_mfma_f32_32x32x16_bf16 v[52:67], v[184:187], v[192:195], v[52:67]
	v_mfma_f32_32x32x16_bf16 v[36:51], v[188:191], v[192:195], v[36:51]
	v_mfma_f32_32x32x16_bf16 v[20:35], v[184:187], v[198:201], v[20:35]
	v_mfma_f32_32x32x16_bf16 v[4:19], v[188:191], v[198:201], v[4:19]
	v_mfma_f32_32x32x16_bf16 v[52:67], v[218:221], v[226:229], v[52:67]
	v_mfma_f32_32x32x16_bf16 v[36:51], v[222:225], v[226:229], v[36:51]
	v_mfma_f32_32x32x16_bf16 v[20:35], v[218:221], v[230:233], v[20:35]
	v_mfma_f32_32x32x16_bf16 v[4:19], v[222:225], v[230:233], v[4:19]
	v_readlane_b32 s10, v253, 26
	v_readlane_b32 s11, v253, 27
	v_or_b32_e32 v68, s7, v114
	v_mov_b32_e32 v88, s10
	v_mov_b32_e32 v89, s31
	v_mov_b32_e32 v90, s29
	v_mov_b32_e32 v91, s30
	v_add_u32_e32 v84, s6, v113
	v_min_i32_e32 v69, 0x8000, v84
	s_mov_b32 s6, 0x8000
	v_ashrrev_i32_e32 v69, 12, v69
	v_cmp_gt_i32_e32 vcc, s6, v84
	v_readlane_b32 s6, v253, 28
	v_mul_hi_i32_i24_e32 v71, 0x6000, v69
	v_mul_i32_i24_e32 v70, 0x6000, v69
	v_add_u32_e32 v69, 0xffff8000, v84
	v_ashrrev_i32_e32 v72, 31, v84
	v_readlane_b32 s7, v253, 29
	v_cndmask_b32_e32 v73, 0, v72, vcc
	v_cndmask_b32_e32 v72, v69, v84, vcc
	v_mov_b32_e32 v85, s7
	v_mov_b32_e32 v86, s11
	v_mov_b32_e32 v87, s6
	v_mov_b32_e32 v92, s28
	v_ashrrev_i32_e32 v69, 31, v68
	v_lshl_add_u64 v[70:71], s[0:1], 0, v[70:71]
	v_cndmask_b32_e32 v75, v85, v86, vcc
	v_cndmask_b32_e32 v74, v87, v88, vcc
	v_lshlrev_b64 v[72:73], 12, v[72:73]
	v_cndmask_b32_e32 v77, v89, v90, vcc
	v_cndmask_b32_e32 v76, v91, v92, vcc
	v_lshlrev_b64 v[68:69], 2, v[68:69]
	v_lshl_add_u64 v[74:75], v[74:75], 0, v[72:73]
	v_lshl_add_u64 v[72:73], v[76:77], 0, v[72:73]
	v_lshl_add_u64 v[78:79], v[70:71], 0, v[68:69]
	v_lshl_add_u64 v[80:81], v[74:75], 0, v[68:69]
	v_lshl_add_u64 v[82:83], v[72:73], 0, v[68:69]
	global_load_dwordx4 v[70:73], v[78:79], off
	global_load_dwordx4 v[74:77], v[80:81], off
	s_movk_i32 s6, 0x7fe0
	v_cmp_gt_i32_e32 vcc, s6, v84
	v_readlane_b32 s6, v252, 40
	s_add_i32 s8, s8, s6
	s_cmpk_gt_i32 s8, 0x7ff
	v_readlane_b32 s7, v252, 41
	s_waitcnt vmcnt(0)
;   template <int MF> DI void operator()(f32x16 (&acc)[MF][2], int mb, int nb, int l31, int h) const {
;     ...
;     for (int mi = 0; mi < MF; ++mi) {
;       const int row = mb + mi * 32 + l31;
;       const float* gr = gate + (size_t)modrow(row) * 6144;
;       const float* rp = row < TL ? res_lat + (size_t)row * D : res_ctx + (size_t)(row - TL) * D;
;       float* op = row < TL ? out_lat + (size_t)row * D : out_ctx + (size_t)(row - TL) * D;
; #pragma unroll
;       for (int g4 = 0; g4 < 4; ++g4)
; #pragma unroll
;         for (int ni = 0; ni < 2; ++ni) {
;           const int col0 = nb + 16 * g4 + 8 * h + 4 * ni;
;           const float4 gt = *(const float4*)(gr + col0);
;           const float4 rv = *(const float4*)(rp + col0);
;           *(float4*)(op + col0) = make_float4(rv.x + gt.x * acc[mi][ni][4 * g4], rv.y + gt.y * acc[mi][ni][4 * g4 + 1], rv.z + gt.z * acc[mi][ni][4 * g4 + 2], rv.w + gt.w * acc[mi][ni][4 * g4 + 3]);
;         }
;     }
	s_nop 9
	v_fma_f32 v52, v52, v70, v74
	v_fma_f32 v53, v53, v71, v75
	v_fma_f32 v54, v54, v72, v76
	v_fma_f32 v55, v55, v73, v77
	global_store_dwordx4 v[82:83], v[52:55], off
	global_load_dwordx4 v[52:55], v[78:79], off offset:16
	s_nop 0
	global_load_dwordx4 v[70:73], v[80:81], off offset:16
	s_waitcnt vmcnt(0)
	s_nop 9
	v_fma_f32 v36, v36, v52, v70
	v_fma_f32 v37, v37, v53, v71
	v_fma_f32 v38, v38, v54, v72
	v_fma_f32 v39, v39, v55, v73
	global_store_dwordx4 v[82:83], v[36:39], off offset:16
	global_load_dwordx4 v[36:39], v[78:79], off offset:64
	s_nop 0
	global_load_dwordx4 v[52:55], v[80:81], off offset:64
	s_waitcnt vmcnt(0)
	v_fma_f32 v36, v56, v36, v52
	v_fma_f32 v37, v57, v37, v53
	v_fma_f32 v38, v58, v38, v54
	v_fma_f32 v39, v59, v39, v55
	global_store_dwordx4 v[82:83], v[36:39], off offset:64
	global_load_dwordx4 v[36:39], v[78:79], off offset:80
	s_nop 0
	global_load_dwordx4 v[52:55], v[80:81], off offset:80
	s_waitcnt vmcnt(0)
	v_fma_f32 v36, v40, v36, v52
	v_fma_f32 v37, v41, v37, v53
	v_fma_f32 v38, v42, v38, v54
	v_fma_f32 v39, v43, v39, v55
	global_store_dwordx4 v[82:83], v[36:39], off offset:80
	global_load_dwordx4 v[36:39], v[78:79], off offset:128
	s_nop 0
	global_load_dwordx4 v[40:43], v[80:81], off offset:128
	s_waitcnt vmcnt(0)
	v_fma_f32 v36, v60, v36, v40
	v_fma_f32 v37, v61, v37, v41
	v_fma_f32 v38, v62, v38, v42
	v_fma_f32 v39, v63, v39, v43
	global_store_dwordx4 v[82:83], v[36:39], off offset:128
	global_load_dwordx4 v[36:39], v[78:79], off offset:144
	s_nop 0
	global_load_dwordx4 v[40:43], v[80:81], off offset:144
	s_waitcnt vmcnt(0)
	v_pk_fma_f32 v[36:37], v[44:45], v[36:37], v[40:41]
	v_pk_fma_f32 v[38:39], v[46:47], v[38:39], v[42:43]
	global_store_dwordx4 v[82:83], v[36:39], off offset:144
	global_load_dwordx4 v[36:39], v[78:79], off offset:192
	s_nop 0
	global_load_dwordx4 v[40:43], v[80:81], off offset:192
	s_waitcnt vmcnt(0)
	v_pk_fma_f32 v[36:37], v[64:65], v[36:37], v[40:41]
	v_pk_fma_f32 v[38:39], v[66:67], v[38:39], v[42:43]
	global_store_dwordx4 v[82:83], v[36:39], off offset:192
	global_load_dwordx4 v[36:39], v[78:79], off offset:208
	s_nop 0
	global_load_dwordx4 v[40:43], v[80:81], off offset:208
	s_waitcnt vmcnt(0)
	v_pk_fma_f32 v[36:37], v[48:49], v[36:37], v[40:41]
	v_pk_fma_f32 v[38:39], v[50:51], v[38:39], v[42:43]
	v_or_b32_e32 v42, 32, v84
	global_store_dwordx4 v[82:83], v[36:39], off offset:208
	v_cndmask_b32_e32 v41, v89, v90, vcc
	v_cndmask_b32_e32 v40, v91, v92, vcc
	v_ashrrev_i32_e32 v36, 31, v42
	v_add_u32_e32 v38, 0xffff8020, v84
	v_cndmask_b32_e32 v37, 0, v36, vcc
	v_cndmask_b32_e32 v36, v38, v42, vcc
	v_cndmask_b32_e32 v39, v85, v86, vcc
	v_cndmask_b32_e32 v38, v87, v88, vcc
	v_lshlrev_b64 v[36:37], 12, v[36:37]
	v_lshl_add_u64 v[38:39], v[38:39], 0, v[36:37]
	v_lshl_add_u64 v[36:37], v[40:41], 0, v[36:37]
	v_min_i32_e32 v40, 0x8000, v42
	v_ashrrev_i32_e32 v40, 12, v40
	v_mul_hi_i32_i24_e32 v41, 0x6000, v40
	v_mul_i32_i24_e32 v40, 0x6000, v40
	v_lshl_add_u64 v[40:41], s[0:1], 0, v[40:41]
	v_lshl_add_u64 v[44:45], v[40:41], 0, v[68:69]
	v_lshl_add_u64 v[46:47], v[38:39], 0, v[68:69]
	v_lshl_add_u64 v[48:49], v[36:37], 0, v[68:69]
	global_load_dwordx4 v[36:39], v[44:45], off
	global_load_dwordx4 v[40:43], v[46:47], off
	s_waitcnt vmcnt(0)
	v_pk_fma_f32 v[20:21], v[20:21], v[36:37], v[40:41]
	v_pk_fma_f32 v[22:23], v[22:23], v[38:39], v[42:43]
	global_store_dwordx4 v[48:49], v[20:23], off
	global_load_dwordx4 v[20:23], v[44:45], off offset:16
	s_nop 0
	global_load_dwordx4 v[36:39], v[46:47], off offset:16
	s_waitcnt vmcnt(0)
	v_pk_fma_f32 v[4:5], v[4:5], v[20:21], v[36:37]
	v_pk_fma_f32 v[6:7], v[6:7], v[22:23], v[38:39]
	global_store_dwordx4 v[48:49], v[4:7], off offset:16
	global_load_dwordx4 v[4:7], v[44:45], off offset:64
	s_nop 0
	global_load_dwordx4 v[20:23], v[46:47], off offset:64
	s_waitcnt vmcnt(0)
	v_pk_fma_f32 v[4:5], v[24:25], v[4:5], v[20:21]
	v_pk_fma_f32 v[6:7], v[26:27], v[6:7], v[22:23]
	global_store_dwordx4 v[48:49], v[4:7], off offset:64
	global_load_dwordx4 v[4:7], v[44:45], off offset:80
	s_nop 0
	global_load_dwordx4 v[20:23], v[46:47], off offset:80
	s_waitcnt vmcnt(0)
	v_pk_fma_f32 v[4:5], v[8:9], v[4:5], v[20:21]
	v_pk_fma_f32 v[6:7], v[10:11], v[6:7], v[22:23]
	global_store_dwordx4 v[48:49], v[4:7], off offset:80
	global_load_dwordx4 v[4:7], v[44:45], off offset:128
	s_nop 0
	global_load_dwordx4 v[8:11], v[46:47], off offset:128
	s_waitcnt vmcnt(0)
	v_pk_fma_f32 v[4:5], v[28:29], v[4:5], v[8:9]
	v_pk_fma_f32 v[6:7], v[30:31], v[6:7], v[10:11]
	global_store_dwordx4 v[48:49], v[4:7], off offset:128
	global_load_dwordx4 v[4:7], v[44:45], off offset:144
	s_nop 0
	global_load_dwordx4 v[8:11], v[46:47], off offset:144
	s_waitcnt vmcnt(0)
	v_pk_fma_f32 v[4:5], v[12:13], v[4:5], v[8:9]
	v_pk_fma_f32 v[6:7], v[14:15], v[6:7], v[10:11]
	global_store_dwordx4 v[48:49], v[4:7], off offset:144
	global_load_dwordx4 v[4:7], v[44:45], off offset:192
	s_nop 0
	global_load_dwordx4 v[8:11], v[46:47], off offset:192
	s_waitcnt vmcnt(0)
	v_pk_fma_f32 v[4:5], v[32:33], v[4:5], v[8:9]
	v_pk_fma_f32 v[6:7], v[34:35], v[6:7], v[10:11]
	global_store_dwordx4 v[48:49], v[4:7], off offset:192
	global_load_dwordx4 v[4:7], v[44:45], off offset:208
	s_nop 0
	global_load_dwordx4 v[8:11], v[46:47], off offset:208
	s_waitcnt vmcnt(0)
	v_pk_fma_f32 v[4:5], v[16:17], v[4:5], v[8:9]
	v_pk_fma_f32 v[6:7], v[18:19], v[6:7], v[10:11]
	global_store_dwordx4 v[48:49], v[4:7], off offset:208
	s_cbranch_scc0 .LBB0_305
